# GINPROJ dt-tile epilogue: 64 inlined log1pf expansions replaced by short f32 log1p (log(u)*e/(u-1)); f32 throughout
# speedup vs baseline: 1.0277x; 1.0277x over previous
;     __device__ __forceinline__ void operator()(const AccT& acc, const pg8::Unit& u, int wr, int wc, int fr, int fq) const {
;     ...
;                         const int row = row0 + ai * 128 + m * 16;
;                         f32x4 v0 = acc[ai][0][m][0] + b0, v1 = acc[ai][0][m][1] + b1;
; #pragma unroll
;                         for (int e = 0; e < 4; ++e) { v0[e] = v0[e] > 20.f ? v0[e] : log1pf(__expf(v0[e])); v1[e] = v1[e] > 20.f ? v1[e] : log1pf(__expf(v1[e])); }
;                         *(f32x4*)(DTS + (size_t)row * 32 + 8 * fq) = v0; *(f32x4*)(DTS + (size_t)row * 32 + 8 * fq + 4) = v1;
.LBB0_311:
	global_load_dwordx4 v[16:19], v[140:141], off
	global_load_dwordx4 v[12:15], v[140:141], off offset:16
	s_waitcnt vmcnt(0)
	v_pk_add_f32 v[72:73], v[72:73], v[16:17]
	s_nop 0
	v_cmp_nlt_f32_e32 vcc, s15, v72
	s_and_saveexec_b64 s[2:3], vcc
	s_cbranch_execz .LBB0_313
	v_mul_f32_e32 v72, 0x3fb8aa3b, v72
	v_exp_f32_e32 v72, v72
	s_nop 0
	v_add_f32_e32 v78, 1.0, v72
	v_add_f32_e32 v80, -1.0, v78
	v_log_f32_e32 v76, v78
	v_rcp_f32_e32 v80, v80
	v_cmp_neq_f32_e32 vcc, 1.0, v78
	v_mul_f32_e32 v76, 0x3f317218, v76
	v_mul_f32_e32 v80, v72, v80
	v_mul_f32_e32 v76, v76, v80
	v_cndmask_b32_e32 v72, v72, v76, vcc
.LBB0_313:
	s_or_b64 exec, exec, s[2:3]
	v_pk_add_f32 v[68:69], v[68:69], v[12:13]
	s_nop 0
	v_cmp_nlt_f32_e32 vcc, s15, v68
	s_and_saveexec_b64 s[2:3], vcc
	s_cbranch_execz .LBB0_315
	v_mul_f32_e32 v68, 0x3fb8aa3b, v68
	v_exp_f32_e32 v68, v68
	s_nop 0
	v_add_f32_e32 v78, 1.0, v68
	v_add_f32_e32 v80, -1.0, v78
	v_log_f32_e32 v76, v78
	v_rcp_f32_e32 v80, v80
	v_cmp_neq_f32_e32 vcc, 1.0, v78
	v_mul_f32_e32 v76, 0x3f317218, v76
	v_mul_f32_e32 v80, v68, v80
	v_mul_f32_e32 v76, v76, v80
	v_cndmask_b32_e32 v68, v68, v76, vcc
.LBB0_315:
	s_or_b64 exec, exec, s[2:3]
	v_pk_add_f32 v[74:75], v[74:75], v[18:19]
	v_cmp_nlt_f32_e32 vcc, s15, v73
	s_and_saveexec_b64 s[2:3], vcc
	s_cbranch_execz .LBB0_317
	v_mul_f32_e32 v73, 0x3fb8aa3b, v73
	v_exp_f32_e32 v73, v73
	s_nop 0
	v_add_f32_e32 v78, 1.0, v73
	v_add_f32_e32 v80, -1.0, v78
	v_log_f32_e32 v76, v78
	v_rcp_f32_e32 v80, v80
	v_cmp_neq_f32_e32 vcc, 1.0, v78
	v_mul_f32_e32 v76, 0x3f317218, v76
	v_mul_f32_e32 v80, v73, v80
	v_mul_f32_e32 v76, v76, v80
	v_cndmask_b32_e32 v73, v73, v76, vcc
.LBB0_317:
	s_or_b64 exec, exec, s[2:3]
	v_pk_add_f32 v[70:71], v[70:71], v[14:15]
	v_cmp_nlt_f32_e32 vcc, s15, v69
	s_and_saveexec_b64 s[2:3], vcc
	s_cbranch_execz .LBB0_408
	v_mul_f32_e32 v69, 0x3fb8aa3b, v69
	v_exp_f32_e32 v69, v69
	s_nop 0
	v_add_f32_e32 v78, 1.0, v69
	v_add_f32_e32 v80, -1.0, v78
	v_log_f32_e32 v76, v78
	v_rcp_f32_e32 v80, v80
	v_cmp_neq_f32_e32 vcc, 1.0, v78
	v_mul_f32_e32 v76, 0x3f317218, v76
	v_mul_f32_e32 v80, v69, v80
	v_mul_f32_e32 v76, v76, v80
	v_cndmask_b32_e32 v69, v69, v76, vcc
	s_or_b64 exec, exec, s[2:3]
	v_cmp_nlt_f32_e32 vcc, s15, v74
	s_and_saveexec_b64 s[2:3], vcc
	s_cbranch_execnz .LBB0_409

;     __device__ __forceinline__ void operator()(const AccT& acc, const pg8::Unit& u, int wr, int wc, int fr, int fq) const {
;     ...
;                         const int row = row0 + ai * 128 + m * 16;
;                         f32x4 v0 = acc[ai][0][m][0] + b0, v1 = acc[ai][0][m][1] + b1;
; #pragma unroll
;                         for (int e = 0; e < 4; ++e) { v0[e] = v0[e] > 20.f ? v0[e] : log1pf(__expf(v0[e])); v1[e] = v1[e] > 20.f ? v1[e] : log1pf(__expf(v1[e])); }
;                         *(f32x4*)(DTS + (size_t)row * 32 + 8 * fq) = v0; *(f32x4*)(DTS + (size_t)row * 32 + 8 * fq + 4) = v1;
.LBB0_320:
	v_mul_f32_e32 v70, 0x3fb8aa3b, v70
	v_exp_f32_e32 v70, v70
	s_nop 0
	v_add_f32_e32 v78, 1.0, v70
	v_add_f32_e32 v80, -1.0, v78
	v_log_f32_e32 v76, v78
	v_rcp_f32_e32 v80, v80
	v_cmp_neq_f32_e32 vcc, 1.0, v78
	v_mul_f32_e32 v76, 0x3f317218, v76
	v_mul_f32_e32 v80, v70, v80
	v_mul_f32_e32 v76, v76, v80
	v_cndmask_b32_e32 v70, v70, v76, vcc
	s_or_b64 exec, exec, s[2:3]
	v_cmp_nlt_f32_e32 vcc, s15, v75
	s_and_saveexec_b64 s[2:3], vcc
	s_cbranch_execnz .LBB0_411

;     __device__ __forceinline__ void operator()(const AccT& acc, const pg8::Unit& u, int wr, int wc, int fr, int fq) const {
;     ...
;                         const int row = row0 + ai * 128 + m * 16;
;                         f32x4 v0 = acc[ai][0][m][0] + b0, v1 = acc[ai][0][m][1] + b1;
; #pragma unroll
;                         for (int e = 0; e < 4; ++e) { v0[e] = v0[e] > 20.f ? v0[e] : log1pf(__expf(v0[e])); v1[e] = v1[e] > 20.f ? v1[e] : log1pf(__expf(v1[e])); }
;                         *(f32x4*)(DTS + (size_t)row * 32 + 8 * fq) = v0; *(f32x4*)(DTS + (size_t)row * 32 + 8 * fq + 4) = v1;
.LBB0_322:
	v_mul_f32_e32 v71, 0x3fb8aa3b, v71
	v_exp_f32_e32 v71, v71
	s_nop 0
	v_add_f32_e32 v78, 1.0, v71
	v_add_f32_e32 v80, -1.0, v78
	v_log_f32_e32 v76, v78
	v_rcp_f32_e32 v80, v80
	v_cmp_neq_f32_e32 vcc, 1.0, v78
	v_mul_f32_e32 v76, 0x3f317218, v76
	v_mul_f32_e32 v80, v71, v80
	v_mul_f32_e32 v76, v76, v80
	v_cndmask_b32_e32 v71, v71, v76, vcc
.LBB0_323:
	s_or_b64 exec, exec, s[2:3]
	v_ashrrev_i32_e32 v147, 31, v146
	v_lshlrev_b64 v[76:77], 7, v[146:147]
	v_pk_add_f32 v[64:65], v[64:65], v[16:17]
	v_lshl_add_u64 v[76:77], v[138:139], 0, v[76:77]
	v_cmp_nlt_f32_e32 vcc, s15, v64
	global_store_dwordx4 v[76:77], v[72:75], off
	global_store_dwordx4 v[76:77], v[68:71], off offset:16
	s_and_saveexec_b64 s[2:3], vcc
	s_cbranch_execz .LBB0_325
	v_mul_f32_e32 v64, 0x3fb8aa3b, v64
	v_exp_f32_e32 v64, v64
	s_nop 0
	v_add_f32_e32 v70, 1.0, v64
	v_add_f32_e32 v72, -1.0, v70
	v_log_f32_e32 v68, v70
	v_rcp_f32_e32 v72, v72
	v_cmp_neq_f32_e32 vcc, 1.0, v70
	v_mul_f32_e32 v68, 0x3f317218, v68
	v_mul_f32_e32 v72, v64, v72
	v_mul_f32_e32 v68, v68, v72
	v_cndmask_b32_e32 v64, v64, v68, vcc
.LBB0_325:
	s_or_b64 exec, exec, s[2:3]
	v_pk_add_f32 v[60:61], v[60:61], v[12:13]
	s_nop 0
	v_cmp_nlt_f32_e32 vcc, s15, v60
	s_and_saveexec_b64 s[2:3], vcc
	s_cbranch_execz .LBB0_327
	v_mul_f32_e32 v60, 0x3fb8aa3b, v60
	v_exp_f32_e32 v60, v60
	s_nop 0
	v_add_f32_e32 v70, 1.0, v60
	v_add_f32_e32 v72, -1.0, v70
	v_log_f32_e32 v68, v70
	v_rcp_f32_e32 v72, v72
	v_cmp_neq_f32_e32 vcc, 1.0, v70
	v_mul_f32_e32 v68, 0x3f317218, v68
	v_mul_f32_e32 v72, v60, v72
	v_mul_f32_e32 v68, v68, v72
	v_cndmask_b32_e32 v60, v60, v68, vcc
.LBB0_327:
	s_or_b64 exec, exec, s[2:3]
	v_pk_add_f32 v[66:67], v[66:67], v[18:19]
	v_cmp_nlt_f32_e32 vcc, s15, v65
	s_and_saveexec_b64 s[2:3], vcc
	s_cbranch_execz .LBB0_329
	v_mul_f32_e32 v65, 0x3fb8aa3b, v65
	v_exp_f32_e32 v65, v65
	s_nop 0
	v_add_f32_e32 v70, 1.0, v65
	v_add_f32_e32 v72, -1.0, v70
	v_log_f32_e32 v68, v70
	v_rcp_f32_e32 v72, v72
	v_cmp_neq_f32_e32 vcc, 1.0, v70
	v_mul_f32_e32 v68, 0x3f317218, v68
	v_mul_f32_e32 v72, v65, v72
	v_mul_f32_e32 v68, v68, v72
	v_cndmask_b32_e32 v65, v65, v68, vcc
.LBB0_329:
	s_or_b64 exec, exec, s[2:3]
	v_pk_add_f32 v[62:63], v[62:63], v[14:15]
	v_cmp_nlt_f32_e32 vcc, s15, v61
	s_and_saveexec_b64 s[2:3], vcc
	s_cbranch_execz .LBB0_412
	v_mul_f32_e32 v61, 0x3fb8aa3b, v61
	v_exp_f32_e32 v61, v61
	s_nop 0
	v_add_f32_e32 v70, 1.0, v61
	v_add_f32_e32 v72, -1.0, v70
	v_log_f32_e32 v68, v70
	v_rcp_f32_e32 v72, v72
	v_cmp_neq_f32_e32 vcc, 1.0, v70
	v_mul_f32_e32 v68, 0x3f317218, v68
	v_mul_f32_e32 v72, v61, v72
	v_mul_f32_e32 v68, v68, v72
	v_cndmask_b32_e32 v61, v61, v68, vcc
	s_or_b64 exec, exec, s[2:3]
	v_cmp_nlt_f32_e32 vcc, s15, v66
	s_and_saveexec_b64 s[2:3], vcc
	s_cbranch_execnz .LBB0_413

;     __device__ __forceinline__ void operator()(const AccT& acc, const pg8::Unit& u, int wr, int wc, int fr, int fq) const {
;     ...
;                         const int row = row0 + ai * 128 + m * 16;
;                         f32x4 v0 = acc[ai][0][m][0] + b0, v1 = acc[ai][0][m][1] + b1;
; #pragma unroll
;                         for (int e = 0; e < 4; ++e) { v0[e] = v0[e] > 20.f ? v0[e] : log1pf(__expf(v0[e])); v1[e] = v1[e] > 20.f ? v1[e] : log1pf(__expf(v1[e])); }
;                         *(f32x4*)(DTS + (size_t)row * 32 + 8 * fq) = v0; *(f32x4*)(DTS + (size_t)row * 32 + 8 * fq + 4) = v1;
.LBB0_332:
	v_mul_f32_e32 v62, 0x3fb8aa3b, v62
	v_exp_f32_e32 v62, v62
	s_nop 0
	v_add_f32_e32 v70, 1.0, v62
	v_add_f32_e32 v72, -1.0, v70
	v_log_f32_e32 v68, v70
	v_rcp_f32_e32 v72, v72
	v_cmp_neq_f32_e32 vcc, 1.0, v70
	v_mul_f32_e32 v68, 0x3f317218, v68
	v_mul_f32_e32 v72, v62, v72
	v_mul_f32_e32 v68, v68, v72
	v_cndmask_b32_e32 v62, v62, v68, vcc
	s_or_b64 exec, exec, s[2:3]
	v_cmp_nlt_f32_e32 vcc, s15, v67
	s_and_saveexec_b64 s[2:3], vcc
	s_cbranch_execnz .LBB0_415

;     __device__ __forceinline__ void operator()(const AccT& acc, const pg8::Unit& u, int wr, int wc, int fr, int fq) const {
;     ...
;                         const int row = row0 + ai * 128 + m * 16;
;                         f32x4 v0 = acc[ai][0][m][0] + b0, v1 = acc[ai][0][m][1] + b1;
; #pragma unroll
;                         for (int e = 0; e < 4; ++e) { v0[e] = v0[e] > 20.f ? v0[e] : log1pf(__expf(v0[e])); v1[e] = v1[e] > 20.f ? v1[e] : log1pf(__expf(v1[e])); }
;                         *(f32x4*)(DTS + (size_t)row * 32 + 8 * fq) = v0; *(f32x4*)(DTS + (size_t)row * 32 + 8 * fq + 4) = v1;
.LBB0_334:
	v_mul_f32_e32 v63, 0x3fb8aa3b, v63
	v_exp_f32_e32 v63, v63
	s_nop 0
	v_add_f32_e32 v70, 1.0, v63
	v_add_f32_e32 v72, -1.0, v70
	v_log_f32_e32 v68, v70
	v_rcp_f32_e32 v72, v72
	v_cmp_neq_f32_e32 vcc, 1.0, v70
	v_mul_f32_e32 v68, 0x3f317218, v68
	v_mul_f32_e32 v72, v63, v72
	v_mul_f32_e32 v68, v68, v72
	v_cndmask_b32_e32 v63, v63, v68, vcc
.LBB0_335:
	s_or_b64 exec, exec, s[2:3]
	v_or_b32_e32 v68, 16, v146
	v_ashrrev_i32_e32 v69, 31, v68
	v_lshlrev_b64 v[68:69], 7, v[68:69]
	v_pk_add_f32 v[56:57], v[56:57], v[16:17]
	v_lshl_add_u64 v[68:69], v[138:139], 0, v[68:69]
	v_cmp_nlt_f32_e32 vcc, s15, v56
	global_store_dwordx4 v[68:69], v[64:67], off
	global_store_dwordx4 v[68:69], v[60:63], off offset:16
	s_and_saveexec_b64 s[2:3], vcc
	s_cbranch_execz .LBB0_337
	v_mul_f32_e32 v56, 0x3fb8aa3b, v56
	v_exp_f32_e32 v56, v56
	s_nop 0
	v_add_f32_e32 v62, 1.0, v56
	v_add_f32_e32 v64, -1.0, v62
	v_log_f32_e32 v60, v62
	v_rcp_f32_e32 v64, v64
	v_cmp_neq_f32_e32 vcc, 1.0, v62
	v_mul_f32_e32 v60, 0x3f317218, v60
	v_mul_f32_e32 v64, v56, v64
	v_mul_f32_e32 v60, v60, v64
	v_cndmask_b32_e32 v56, v56, v60, vcc
.LBB0_337:
	s_or_b64 exec, exec, s[2:3]
	v_pk_add_f32 v[52:53], v[52:53], v[12:13]
	s_nop 0
	v_cmp_nlt_f32_e32 vcc, s15, v52
	s_and_saveexec_b64 s[2:3], vcc
	s_cbranch_execz .LBB0_339
	v_mul_f32_e32 v52, 0x3fb8aa3b, v52
	v_exp_f32_e32 v52, v52
	s_nop 0
	v_add_f32_e32 v62, 1.0, v52
	v_add_f32_e32 v64, -1.0, v62
	v_log_f32_e32 v60, v62
	v_rcp_f32_e32 v64, v64
	v_cmp_neq_f32_e32 vcc, 1.0, v62
	v_mul_f32_e32 v60, 0x3f317218, v60
	v_mul_f32_e32 v64, v52, v64
	v_mul_f32_e32 v60, v60, v64
	v_cndmask_b32_e32 v52, v52, v60, vcc
.LBB0_339:
	s_or_b64 exec, exec, s[2:3]
	v_pk_add_f32 v[58:59], v[58:59], v[18:19]
	v_cmp_nlt_f32_e32 vcc, s15, v57
	s_and_saveexec_b64 s[2:3], vcc
	s_cbranch_execz .LBB0_341
	v_mul_f32_e32 v57, 0x3fb8aa3b, v57
	v_exp_f32_e32 v57, v57
	s_nop 0
	v_add_f32_e32 v62, 1.0, v57
	v_add_f32_e32 v64, -1.0, v62
	v_log_f32_e32 v60, v62
	v_rcp_f32_e32 v64, v64
	v_cmp_neq_f32_e32 vcc, 1.0, v62
	v_mul_f32_e32 v60, 0x3f317218, v60
	v_mul_f32_e32 v64, v57, v64
	v_mul_f32_e32 v60, v60, v64
	v_cndmask_b32_e32 v57, v57, v60, vcc
.LBB0_341:
	s_or_b64 exec, exec, s[2:3]
	v_pk_add_f32 v[54:55], v[54:55], v[14:15]
	v_cmp_nlt_f32_e32 vcc, s15, v53
	s_and_saveexec_b64 s[2:3], vcc
	s_cbranch_execz .LBB0_416
	v_mul_f32_e32 v53, 0x3fb8aa3b, v53
	v_exp_f32_e32 v53, v53
	s_nop 0
	v_add_f32_e32 v62, 1.0, v53
	v_add_f32_e32 v64, -1.0, v62
	v_log_f32_e32 v60, v62
	v_rcp_f32_e32 v64, v64
	v_cmp_neq_f32_e32 vcc, 1.0, v62
	v_mul_f32_e32 v60, 0x3f317218, v60
	v_mul_f32_e32 v64, v53, v64
	v_mul_f32_e32 v60, v60, v64
	v_cndmask_b32_e32 v53, v53, v60, vcc
	s_or_b64 exec, exec, s[2:3]
	v_cmp_nlt_f32_e32 vcc, s15, v58
	s_and_saveexec_b64 s[2:3], vcc
	s_cbranch_execnz .LBB0_417

;     __device__ __forceinline__ void operator()(const AccT& acc, const pg8::Unit& u, int wr, int wc, int fr, int fq) const {
;     ...
;                         const int row = row0 + ai * 128 + m * 16;
;                         f32x4 v0 = acc[ai][0][m][0] + b0, v1 = acc[ai][0][m][1] + b1;
; #pragma unroll
;                         for (int e = 0; e < 4; ++e) { v0[e] = v0[e] > 20.f ? v0[e] : log1pf(__expf(v0[e])); v1[e] = v1[e] > 20.f ? v1[e] : log1pf(__expf(v1[e])); }
;                         *(f32x4*)(DTS + (size_t)row * 32 + 8 * fq) = v0; *(f32x4*)(DTS + (size_t)row * 32 + 8 * fq + 4) = v1;
.LBB0_344:
	v_mul_f32_e32 v54, 0x3fb8aa3b, v54
	v_exp_f32_e32 v54, v54
	s_nop 0
	v_add_f32_e32 v62, 1.0, v54
	v_add_f32_e32 v64, -1.0, v62
	v_log_f32_e32 v60, v62
	v_rcp_f32_e32 v64, v64
	v_cmp_neq_f32_e32 vcc, 1.0, v62
	v_mul_f32_e32 v60, 0x3f317218, v60
	v_mul_f32_e32 v64, v54, v64
	v_mul_f32_e32 v60, v60, v64
	v_cndmask_b32_e32 v54, v54, v60, vcc
	s_or_b64 exec, exec, s[2:3]
	v_cmp_nlt_f32_e32 vcc, s15, v59
	s_and_saveexec_b64 s[2:3], vcc
	s_cbranch_execnz .LBB0_419

;     __device__ __forceinline__ void operator()(const AccT& acc, const pg8::Unit& u, int wr, int wc, int fr, int fq) const {
;     ...
;                         const int row = row0 + ai * 128 + m * 16;
;                         f32x4 v0 = acc[ai][0][m][0] + b0, v1 = acc[ai][0][m][1] + b1;
; #pragma unroll
;                         for (int e = 0; e < 4; ++e) { v0[e] = v0[e] > 20.f ? v0[e] : log1pf(__expf(v0[e])); v1[e] = v1[e] > 20.f ? v1[e] : log1pf(__expf(v1[e])); }
;                         *(f32x4*)(DTS + (size_t)row * 32 + 8 * fq) = v0; *(f32x4*)(DTS + (size_t)row * 32 + 8 * fq + 4) = v1;
.LBB0_346:
	v_mul_f32_e32 v55, 0x3fb8aa3b, v55
	v_exp_f32_e32 v55, v55
	s_nop 0
	v_add_f32_e32 v62, 1.0, v55
	v_add_f32_e32 v64, -1.0, v62
	v_log_f32_e32 v60, v62
	v_rcp_f32_e32 v64, v64
	v_cmp_neq_f32_e32 vcc, 1.0, v62
	v_mul_f32_e32 v60, 0x3f317218, v60
	v_mul_f32_e32 v64, v55, v64
	v_mul_f32_e32 v60, v60, v64
	v_cndmask_b32_e32 v55, v55, v60, vcc
.LBB0_347:
	s_or_b64 exec, exec, s[2:3]
	v_or_b32_e32 v60, 32, v146
	v_ashrrev_i32_e32 v61, 31, v60
	v_lshlrev_b64 v[60:61], 7, v[60:61]
	v_pk_add_f32 v[48:49], v[48:49], v[16:17]
	v_lshl_add_u64 v[60:61], v[138:139], 0, v[60:61]
	v_cmp_nlt_f32_e32 vcc, s15, v48
	global_store_dwordx4 v[60:61], v[56:59], off
	global_store_dwordx4 v[60:61], v[52:55], off offset:16
	s_and_saveexec_b64 s[2:3], vcc
	s_cbranch_execz .LBB0_349
	v_mul_f32_e32 v48, 0x3fb8aa3b, v48
	v_exp_f32_e32 v48, v48
	s_nop 0
	v_add_f32_e32 v54, 1.0, v48
	v_add_f32_e32 v56, -1.0, v54
	v_log_f32_e32 v52, v54
	v_rcp_f32_e32 v56, v56
	v_cmp_neq_f32_e32 vcc, 1.0, v54
	v_mul_f32_e32 v52, 0x3f317218, v52
	v_mul_f32_e32 v56, v48, v56
	v_mul_f32_e32 v52, v52, v56
	v_cndmask_b32_e32 v48, v48, v52, vcc
.LBB0_349:
	s_or_b64 exec, exec, s[2:3]
	v_pk_add_f32 v[44:45], v[44:45], v[12:13]
	s_nop 0
	v_cmp_nlt_f32_e32 vcc, s15, v44
	s_and_saveexec_b64 s[2:3], vcc
	s_cbranch_execz .LBB0_351
	v_mul_f32_e32 v44, 0x3fb8aa3b, v44
	v_exp_f32_e32 v44, v44
	s_nop 0
	v_add_f32_e32 v54, 1.0, v44
	v_add_f32_e32 v56, -1.0, v54
	v_log_f32_e32 v52, v54
	v_rcp_f32_e32 v56, v56
	v_cmp_neq_f32_e32 vcc, 1.0, v54
	v_mul_f32_e32 v52, 0x3f317218, v52
	v_mul_f32_e32 v56, v44, v56
	v_mul_f32_e32 v52, v52, v56
	v_cndmask_b32_e32 v44, v44, v52, vcc
.LBB0_351:
	s_or_b64 exec, exec, s[2:3]
	v_pk_add_f32 v[50:51], v[50:51], v[18:19]
	v_cmp_nlt_f32_e32 vcc, s15, v49
	s_and_saveexec_b64 s[2:3], vcc
	s_cbranch_execz .LBB0_353
	v_mul_f32_e32 v49, 0x3fb8aa3b, v49
	v_exp_f32_e32 v49, v49
	s_nop 0
	v_add_f32_e32 v54, 1.0, v49
	v_add_f32_e32 v56, -1.0, v54
	v_log_f32_e32 v52, v54
	v_rcp_f32_e32 v56, v56
	v_cmp_neq_f32_e32 vcc, 1.0, v54
	v_mul_f32_e32 v52, 0x3f317218, v52
	v_mul_f32_e32 v56, v49, v56
	v_mul_f32_e32 v52, v52, v56
	v_cndmask_b32_e32 v49, v49, v52, vcc
.LBB0_353:
	s_or_b64 exec, exec, s[2:3]
	v_pk_add_f32 v[46:47], v[46:47], v[14:15]
	v_cmp_nlt_f32_e32 vcc, s15, v45
	s_and_saveexec_b64 s[2:3], vcc
	s_cbranch_execz .LBB0_420
	v_mul_f32_e32 v45, 0x3fb8aa3b, v45
	v_exp_f32_e32 v45, v45
	s_nop 0
	v_add_f32_e32 v54, 1.0, v45
	v_add_f32_e32 v56, -1.0, v54
	v_log_f32_e32 v52, v54
	v_rcp_f32_e32 v56, v56
	v_cmp_neq_f32_e32 vcc, 1.0, v54
	v_mul_f32_e32 v52, 0x3f317218, v52
	v_mul_f32_e32 v56, v45, v56
	v_mul_f32_e32 v52, v52, v56
	v_cndmask_b32_e32 v45, v45, v52, vcc
	s_or_b64 exec, exec, s[2:3]
	v_cmp_nlt_f32_e32 vcc, s15, v50
	s_and_saveexec_b64 s[2:3], vcc
	s_cbranch_execnz .LBB0_421

;     __device__ __forceinline__ void operator()(const AccT& acc, const pg8::Unit& u, int wr, int wc, int fr, int fq) const {
;     ...
;                         const int row = row0 + ai * 128 + m * 16;
;                         f32x4 v0 = acc[ai][0][m][0] + b0, v1 = acc[ai][0][m][1] + b1;
; #pragma unroll
;                         for (int e = 0; e < 4; ++e) { v0[e] = v0[e] > 20.f ? v0[e] : log1pf(__expf(v0[e])); v1[e] = v1[e] > 20.f ? v1[e] : log1pf(__expf(v1[e])); }
;                         *(f32x4*)(DTS + (size_t)row * 32 + 8 * fq) = v0; *(f32x4*)(DTS + (size_t)row * 32 + 8 * fq + 4) = v1;
.LBB0_356:
	v_mul_f32_e32 v46, 0x3fb8aa3b, v46
	v_exp_f32_e32 v46, v46
	s_nop 0
	v_add_f32_e32 v54, 1.0, v46
	v_add_f32_e32 v56, -1.0, v54
	v_log_f32_e32 v52, v54
	v_rcp_f32_e32 v56, v56
	v_cmp_neq_f32_e32 vcc, 1.0, v54
	v_mul_f32_e32 v52, 0x3f317218, v52
	v_mul_f32_e32 v56, v46, v56
	v_mul_f32_e32 v52, v52, v56
	v_cndmask_b32_e32 v46, v46, v52, vcc
	s_or_b64 exec, exec, s[2:3]
	v_cmp_nlt_f32_e32 vcc, s15, v51
	s_and_saveexec_b64 s[2:3], vcc
	s_cbranch_execnz .LBB0_423

;     __device__ __forceinline__ void operator()(const AccT& acc, const pg8::Unit& u, int wr, int wc, int fr, int fq) const {
;     ...
;                         const int row = row0 + ai * 128 + m * 16;
;                         f32x4 v0 = acc[ai][0][m][0] + b0, v1 = acc[ai][0][m][1] + b1;
; #pragma unroll
;                         for (int e = 0; e < 4; ++e) { v0[e] = v0[e] > 20.f ? v0[e] : log1pf(__expf(v0[e])); v1[e] = v1[e] > 20.f ? v1[e] : log1pf(__expf(v1[e])); }
;                         *(f32x4*)(DTS + (size_t)row * 32 + 8 * fq) = v0; *(f32x4*)(DTS + (size_t)row * 32 + 8 * fq + 4) = v1;
.LBB0_358:
	v_mul_f32_e32 v47, 0x3fb8aa3b, v47
	v_exp_f32_e32 v47, v47
	s_nop 0
	v_add_f32_e32 v54, 1.0, v47
	v_add_f32_e32 v56, -1.0, v54
	v_log_f32_e32 v52, v54
	v_rcp_f32_e32 v56, v56
	v_cmp_neq_f32_e32 vcc, 1.0, v54
	v_mul_f32_e32 v52, 0x3f317218, v52
	v_mul_f32_e32 v56, v47, v56
	v_mul_f32_e32 v52, v52, v56
	v_cndmask_b32_e32 v47, v47, v52, vcc
.LBB0_359:
	s_or_b64 exec, exec, s[2:3]
	v_or_b32_e32 v52, 48, v146
	v_ashrrev_i32_e32 v53, 31, v52
	v_lshlrev_b64 v[52:53], 7, v[52:53]
	v_pk_add_f32 v[40:41], v[40:41], v[16:17]
	v_lshl_add_u64 v[52:53], v[138:139], 0, v[52:53]
	v_cmp_nlt_f32_e32 vcc, s15, v40
	global_store_dwordx4 v[52:53], v[48:51], off
	global_store_dwordx4 v[52:53], v[44:47], off offset:16
	s_and_saveexec_b64 s[2:3], vcc
	s_cbranch_execz .LBB0_361
	v_mul_f32_e32 v40, 0x3fb8aa3b, v40
	v_exp_f32_e32 v40, v40
	s_nop 0
	v_add_f32_e32 v46, 1.0, v40
	v_add_f32_e32 v48, -1.0, v46
	v_log_f32_e32 v44, v46
	v_rcp_f32_e32 v48, v48
	v_cmp_neq_f32_e32 vcc, 1.0, v46
	v_mul_f32_e32 v44, 0x3f317218, v44
	v_mul_f32_e32 v48, v40, v48
	v_mul_f32_e32 v44, v44, v48
	v_cndmask_b32_e32 v40, v40, v44, vcc
.LBB0_361:
	s_or_b64 exec, exec, s[2:3]
	v_pk_add_f32 v[36:37], v[36:37], v[12:13]
	s_nop 0
	v_cmp_nlt_f32_e32 vcc, s15, v36
	s_and_saveexec_b64 s[2:3], vcc
	s_cbranch_execz .LBB0_363
	v_mul_f32_e32 v36, 0x3fb8aa3b, v36
	v_exp_f32_e32 v36, v36
	s_nop 0
	v_add_f32_e32 v46, 1.0, v36
	v_add_f32_e32 v48, -1.0, v46
	v_log_f32_e32 v44, v46
	v_rcp_f32_e32 v48, v48
	v_cmp_neq_f32_e32 vcc, 1.0, v46
	v_mul_f32_e32 v44, 0x3f317218, v44
	v_mul_f32_e32 v48, v36, v48
	v_mul_f32_e32 v44, v44, v48
	v_cndmask_b32_e32 v36, v36, v44, vcc
.LBB0_363:
	s_or_b64 exec, exec, s[2:3]
	v_pk_add_f32 v[42:43], v[42:43], v[18:19]
	v_cmp_nlt_f32_e32 vcc, s15, v41
	s_and_saveexec_b64 s[2:3], vcc
	s_cbranch_execz .LBB0_365
	v_mul_f32_e32 v41, 0x3fb8aa3b, v41
	v_exp_f32_e32 v41, v41
	s_nop 0
	v_add_f32_e32 v46, 1.0, v41
	v_add_f32_e32 v48, -1.0, v46
	v_log_f32_e32 v44, v46
	v_rcp_f32_e32 v48, v48
	v_cmp_neq_f32_e32 vcc, 1.0, v46
	v_mul_f32_e32 v44, 0x3f317218, v44
	v_mul_f32_e32 v48, v41, v48
	v_mul_f32_e32 v44, v44, v48
	v_cndmask_b32_e32 v41, v41, v44, vcc
.LBB0_365:
	s_or_b64 exec, exec, s[2:3]
	v_pk_add_f32 v[38:39], v[38:39], v[14:15]
	v_cmp_nlt_f32_e32 vcc, s15, v37
	s_and_saveexec_b64 s[2:3], vcc
	s_cbranch_execz .LBB0_424
	v_mul_f32_e32 v37, 0x3fb8aa3b, v37
	v_exp_f32_e32 v37, v37
	s_nop 0
	v_add_f32_e32 v46, 1.0, v37
	v_add_f32_e32 v48, -1.0, v46
	v_log_f32_e32 v44, v46
	v_rcp_f32_e32 v48, v48
	v_cmp_neq_f32_e32 vcc, 1.0, v46
	v_mul_f32_e32 v44, 0x3f317218, v44
	v_mul_f32_e32 v48, v37, v48
	v_mul_f32_e32 v44, v44, v48
	v_cndmask_b32_e32 v37, v37, v44, vcc
	s_or_b64 exec, exec, s[2:3]
	v_cmp_nlt_f32_e32 vcc, s15, v42
	s_and_saveexec_b64 s[2:3], vcc
	s_cbranch_execnz .LBB0_425

;     __device__ __forceinline__ void operator()(const AccT& acc, const pg8::Unit& u, int wr, int wc, int fr, int fq) const {
;     ...
;                         const int row = row0 + ai * 128 + m * 16;
;                         f32x4 v0 = acc[ai][0][m][0] + b0, v1 = acc[ai][0][m][1] + b1;
; #pragma unroll
;                         for (int e = 0; e < 4; ++e) { v0[e] = v0[e] > 20.f ? v0[e] : log1pf(__expf(v0[e])); v1[e] = v1[e] > 20.f ? v1[e] : log1pf(__expf(v1[e])); }
;                         *(f32x4*)(DTS + (size_t)row * 32 + 8 * fq) = v0; *(f32x4*)(DTS + (size_t)row * 32 + 8 * fq + 4) = v1;
.LBB0_368:
	v_mul_f32_e32 v38, 0x3fb8aa3b, v38
	v_exp_f32_e32 v38, v38
	s_nop 0
	v_add_f32_e32 v46, 1.0, v38
	v_add_f32_e32 v48, -1.0, v46
	v_log_f32_e32 v44, v46
	v_rcp_f32_e32 v48, v48
	v_cmp_neq_f32_e32 vcc, 1.0, v46
	v_mul_f32_e32 v44, 0x3f317218, v44
	v_mul_f32_e32 v48, v38, v48
	v_mul_f32_e32 v44, v44, v48
	v_cndmask_b32_e32 v38, v38, v44, vcc
	s_or_b64 exec, exec, s[2:3]
	v_cmp_nlt_f32_e32 vcc, s15, v43
	s_and_saveexec_b64 s[2:3], vcc
	s_cbranch_execnz .LBB0_427

;     __device__ __forceinline__ void operator()(const AccT& acc, const pg8::Unit& u, int wr, int wc, int fr, int fq) const {
;     ...
;                         const int row = row0 + ai * 128 + m * 16;
;                         f32x4 v0 = acc[ai][0][m][0] + b0, v1 = acc[ai][0][m][1] + b1;
; #pragma unroll
;                         for (int e = 0; e < 4; ++e) { v0[e] = v0[e] > 20.f ? v0[e] : log1pf(__expf(v0[e])); v1[e] = v1[e] > 20.f ? v1[e] : log1pf(__expf(v1[e])); }
;                         *(f32x4*)(DTS + (size_t)row * 32 + 8 * fq) = v0; *(f32x4*)(DTS + (size_t)row * 32 + 8 * fq + 4) = v1;
.LBB0_370:
	v_mul_f32_e32 v39, 0x3fb8aa3b, v39
	v_exp_f32_e32 v39, v39
	s_nop 0
	v_add_f32_e32 v46, 1.0, v39
	v_add_f32_e32 v48, -1.0, v46
	v_log_f32_e32 v44, v46
	v_rcp_f32_e32 v48, v48
	v_cmp_neq_f32_e32 vcc, 1.0, v46
	v_mul_f32_e32 v44, 0x3f317218, v44
	v_mul_f32_e32 v48, v39, v48
	v_mul_f32_e32 v44, v44, v48
	v_cndmask_b32_e32 v39, v39, v44, vcc
.LBB0_371:
	s_or_b64 exec, exec, s[2:3]
	v_lshlrev_b64 v[44:45], 7, v[146:147]
	v_lshl_add_u64 v[44:45], v[138:139], 0, v[44:45]
	v_lshl_add_u64 v[46:47], v[44:45], 0, s[84:85]
	v_add_co_u32_e32 v44, vcc, 0x4000, v44
	v_pk_add_f32 v[32:33], v[32:33], v[16:17]
	s_nop 0
	v_addc_co_u32_e32 v45, vcc, 0, v45, vcc
	v_cmp_nlt_f32_e32 vcc, s15, v32
	global_store_dwordx4 v[44:45], v[40:43], off
	global_store_dwordx4 v[46:47], v[36:39], off offset:16
	s_and_saveexec_b64 s[2:3], vcc
	s_cbranch_execz .LBB0_373
	v_mul_f32_e32 v32, 0x3fb8aa3b, v32
	v_exp_f32_e32 v32, v32
	s_nop 0
	v_add_f32_e32 v38, 1.0, v32
	v_add_f32_e32 v40, -1.0, v38
	v_log_f32_e32 v36, v38
	v_rcp_f32_e32 v40, v40
	v_cmp_neq_f32_e32 vcc, 1.0, v38
	v_mul_f32_e32 v36, 0x3f317218, v36
	v_mul_f32_e32 v40, v32, v40
	v_mul_f32_e32 v36, v36, v40
	v_cndmask_b32_e32 v32, v32, v36, vcc
.LBB0_373:
	s_or_b64 exec, exec, s[2:3]
	v_pk_add_f32 v[28:29], v[28:29], v[12:13]
	s_nop 0
	v_cmp_nlt_f32_e32 vcc, s15, v28
	s_and_saveexec_b64 s[2:3], vcc
	s_cbranch_execz .LBB0_375
	v_mul_f32_e32 v28, 0x3fb8aa3b, v28
	v_exp_f32_e32 v28, v28
	s_nop 0
	v_add_f32_e32 v38, 1.0, v28
	v_add_f32_e32 v40, -1.0, v38
	v_log_f32_e32 v36, v38
	v_rcp_f32_e32 v40, v40
	v_cmp_neq_f32_e32 vcc, 1.0, v38
	v_mul_f32_e32 v36, 0x3f317218, v36
	v_mul_f32_e32 v40, v28, v40
	v_mul_f32_e32 v36, v36, v40
	v_cndmask_b32_e32 v28, v28, v36, vcc
.LBB0_375:
	s_or_b64 exec, exec, s[2:3]
	v_pk_add_f32 v[34:35], v[34:35], v[18:19]
	v_cmp_nlt_f32_e32 vcc, s15, v33
	s_and_saveexec_b64 s[2:3], vcc
	s_cbranch_execz .LBB0_377
	v_mul_f32_e32 v33, 0x3fb8aa3b, v33
	v_exp_f32_e32 v33, v33
	s_nop 0
	v_add_f32_e32 v38, 1.0, v33
	v_add_f32_e32 v40, -1.0, v38
	v_log_f32_e32 v36, v38
	v_rcp_f32_e32 v40, v40
	v_cmp_neq_f32_e32 vcc, 1.0, v38
	v_mul_f32_e32 v36, 0x3f317218, v36
	v_mul_f32_e32 v40, v33, v40
	v_mul_f32_e32 v36, v36, v40
	v_cndmask_b32_e32 v33, v33, v36, vcc
.LBB0_377:
	s_or_b64 exec, exec, s[2:3]
	v_pk_add_f32 v[30:31], v[30:31], v[14:15]
	v_cmp_nlt_f32_e32 vcc, s15, v29
	s_and_saveexec_b64 s[2:3], vcc
	s_cbranch_execz .LBB0_428
	v_mul_f32_e32 v29, 0x3fb8aa3b, v29
	v_exp_f32_e32 v29, v29
	s_nop 0
	v_add_f32_e32 v38, 1.0, v29
	v_add_f32_e32 v40, -1.0, v38
	v_log_f32_e32 v36, v38
	v_rcp_f32_e32 v40, v40
	v_cmp_neq_f32_e32 vcc, 1.0, v38
	v_mul_f32_e32 v36, 0x3f317218, v36
	v_mul_f32_e32 v40, v29, v40
	v_mul_f32_e32 v36, v36, v40
	v_cndmask_b32_e32 v29, v29, v36, vcc
	s_or_b64 exec, exec, s[2:3]
	v_cmp_nlt_f32_e32 vcc, s15, v34
	s_and_saveexec_b64 s[2:3], vcc
	s_cbranch_execnz .LBB0_429

;     __device__ __forceinline__ void operator()(const AccT& acc, const pg8::Unit& u, int wr, int wc, int fr, int fq) const {
;     ...
;                         const int row = row0 + ai * 128 + m * 16;
;                         f32x4 v0 = acc[ai][0][m][0] + b0, v1 = acc[ai][0][m][1] + b1;
; #pragma unroll
;                         for (int e = 0; e < 4; ++e) { v0[e] = v0[e] > 20.f ? v0[e] : log1pf(__expf(v0[e])); v1[e] = v1[e] > 20.f ? v1[e] : log1pf(__expf(v1[e])); }
;                         *(f32x4*)(DTS + (size_t)row * 32 + 8 * fq) = v0; *(f32x4*)(DTS + (size_t)row * 32 + 8 * fq + 4) = v1;
.LBB0_380:
	v_mul_f32_e32 v30, 0x3fb8aa3b, v30
	v_exp_f32_e32 v30, v30
	s_nop 0
	v_add_f32_e32 v38, 1.0, v30
	v_add_f32_e32 v40, -1.0, v38
	v_log_f32_e32 v36, v38
	v_rcp_f32_e32 v40, v40
	v_cmp_neq_f32_e32 vcc, 1.0, v38
	v_mul_f32_e32 v36, 0x3f317218, v36
	v_mul_f32_e32 v40, v30, v40
	v_mul_f32_e32 v36, v36, v40
	v_cndmask_b32_e32 v30, v30, v36, vcc
	s_or_b64 exec, exec, s[2:3]
	v_cmp_nlt_f32_e32 vcc, s15, v35
	s_and_saveexec_b64 s[2:3], vcc
	s_cbranch_execnz .LBB0_431

;     __device__ __forceinline__ void operator()(const AccT& acc, const pg8::Unit& u, int wr, int wc, int fr, int fq) const {
;     ...
;                         const int row = row0 + ai * 128 + m * 16;
;                         f32x4 v0 = acc[ai][0][m][0] + b0, v1 = acc[ai][0][m][1] + b1;
; #pragma unroll
;                         for (int e = 0; e < 4; ++e) { v0[e] = v0[e] > 20.f ? v0[e] : log1pf(__expf(v0[e])); v1[e] = v1[e] > 20.f ? v1[e] : log1pf(__expf(v1[e])); }
;                         *(f32x4*)(DTS + (size_t)row * 32 + 8 * fq) = v0; *(f32x4*)(DTS + (size_t)row * 32 + 8 * fq + 4) = v1;
.LBB0_382:
	v_mul_f32_e32 v31, 0x3fb8aa3b, v31
	v_exp_f32_e32 v31, v31
	s_nop 0
	v_add_f32_e32 v38, 1.0, v31
	v_add_f32_e32 v40, -1.0, v38
	v_log_f32_e32 v36, v38
	v_rcp_f32_e32 v40, v40
	v_cmp_neq_f32_e32 vcc, 1.0, v38
	v_mul_f32_e32 v36, 0x3f317218, v36
	v_mul_f32_e32 v40, v31, v40
	v_mul_f32_e32 v36, v36, v40
	v_cndmask_b32_e32 v31, v31, v36, vcc
.LBB0_383:
	s_or_b64 exec, exec, s[2:3]
	v_lshlrev_b64 v[36:37], 7, v[146:147]
	v_lshl_add_u64 v[36:37], v[138:139], 0, v[36:37]
	s_mov_b64 s[2:3], 0x4800
	v_lshl_add_u64 v[38:39], v[36:37], 0, s[2:3]
	v_add_co_u32_e32 v36, vcc, 0x4000, v36
	v_pk_add_f32 v[24:25], v[24:25], v[16:17]
	s_nop 0
	v_addc_co_u32_e32 v37, vcc, 0, v37, vcc
	v_cmp_nlt_f32_e32 vcc, s15, v24
	global_store_dwordx4 v[36:37], v[32:35], off offset:2048
	global_store_dwordx4 v[38:39], v[28:31], off offset:16
	s_and_saveexec_b64 s[2:3], vcc
	s_cbranch_execz .LBB0_385
	v_mul_f32_e32 v24, 0x3fb8aa3b, v24
	v_exp_f32_e32 v24, v24
	s_nop 0
	v_add_f32_e32 v30, 1.0, v24
	v_add_f32_e32 v32, -1.0, v30
	v_log_f32_e32 v28, v30
	v_rcp_f32_e32 v32, v32
	v_cmp_neq_f32_e32 vcc, 1.0, v30
	v_mul_f32_e32 v28, 0x3f317218, v28
	v_mul_f32_e32 v32, v24, v32
	v_mul_f32_e32 v28, v28, v32
	v_cndmask_b32_e32 v24, v24, v28, vcc
.LBB0_385:
	s_or_b64 exec, exec, s[2:3]
	v_pk_add_f32 v[20:21], v[20:21], v[12:13]
	s_nop 0
	v_cmp_nlt_f32_e32 vcc, s15, v20
	s_and_saveexec_b64 s[2:3], vcc
	s_cbranch_execz .LBB0_387
	v_mul_f32_e32 v20, 0x3fb8aa3b, v20
	v_exp_f32_e32 v20, v20
	s_nop 0
	v_add_f32_e32 v30, 1.0, v20
	v_add_f32_e32 v32, -1.0, v30
	v_log_f32_e32 v28, v30
	v_rcp_f32_e32 v32, v32
	v_cmp_neq_f32_e32 vcc, 1.0, v30
	v_mul_f32_e32 v28, 0x3f317218, v28
	v_mul_f32_e32 v32, v20, v32
	v_mul_f32_e32 v28, v28, v32
	v_cndmask_b32_e32 v20, v20, v28, vcc
.LBB0_387:
	s_or_b64 exec, exec, s[2:3]
	v_pk_add_f32 v[26:27], v[26:27], v[18:19]
	v_cmp_nlt_f32_e32 vcc, s15, v25
	s_and_saveexec_b64 s[2:3], vcc
	s_cbranch_execz .LBB0_389
	v_mul_f32_e32 v25, 0x3fb8aa3b, v25
	v_exp_f32_e32 v25, v25
	s_nop 0
	v_add_f32_e32 v30, 1.0, v25
	v_add_f32_e32 v32, -1.0, v30
	v_log_f32_e32 v28, v30
	v_rcp_f32_e32 v32, v32
	v_cmp_neq_f32_e32 vcc, 1.0, v30
	v_mul_f32_e32 v28, 0x3f317218, v28
	v_mul_f32_e32 v32, v25, v32
	v_mul_f32_e32 v28, v28, v32
	v_cndmask_b32_e32 v25, v25, v28, vcc
.LBB0_389:
	s_or_b64 exec, exec, s[2:3]
	v_pk_add_f32 v[22:23], v[22:23], v[14:15]
	v_cmp_nlt_f32_e32 vcc, s15, v21
	s_and_saveexec_b64 s[2:3], vcc
	s_cbranch_execz .LBB0_432
	v_mul_f32_e32 v21, 0x3fb8aa3b, v21
	v_exp_f32_e32 v21, v21
	s_nop 0
	v_add_f32_e32 v30, 1.0, v21
	v_add_f32_e32 v32, -1.0, v30
	v_log_f32_e32 v28, v30
	v_rcp_f32_e32 v32, v32
	v_cmp_neq_f32_e32 vcc, 1.0, v30
	v_mul_f32_e32 v28, 0x3f317218, v28
	v_mul_f32_e32 v32, v21, v32
	v_mul_f32_e32 v28, v28, v32
	v_cndmask_b32_e32 v21, v21, v28, vcc
	s_or_b64 exec, exec, s[2:3]
	v_cmp_nlt_f32_e32 vcc, s15, v26
	s_and_saveexec_b64 s[2:3], vcc
	s_cbranch_execnz .LBB0_433

;     __device__ __forceinline__ void operator()(const AccT& acc, const pg8::Unit& u, int wr, int wc, int fr, int fq) const {
;     ...
;                         const int row = row0 + ai * 128 + m * 16;
;                         f32x4 v0 = acc[ai][0][m][0] + b0, v1 = acc[ai][0][m][1] + b1;
; #pragma unroll
;                         for (int e = 0; e < 4; ++e) { v0[e] = v0[e] > 20.f ? v0[e] : log1pf(__expf(v0[e])); v1[e] = v1[e] > 20.f ? v1[e] : log1pf(__expf(v1[e])); }
;                         *(f32x4*)(DTS + (size_t)row * 32 + 8 * fq) = v0; *(f32x4*)(DTS + (size_t)row * 32 + 8 * fq + 4) = v1;
.LBB0_392:
	v_mul_f32_e32 v22, 0x3fb8aa3b, v22
	v_exp_f32_e32 v22, v22
	s_nop 0
	v_add_f32_e32 v30, 1.0, v22
	v_add_f32_e32 v32, -1.0, v30
	v_log_f32_e32 v28, v30
	v_rcp_f32_e32 v32, v32
	v_cmp_neq_f32_e32 vcc, 1.0, v30
	v_mul_f32_e32 v28, 0x3f317218, v28
	v_mul_f32_e32 v32, v22, v32
	v_mul_f32_e32 v28, v28, v32
	v_cndmask_b32_e32 v22, v22, v28, vcc
	s_or_b64 exec, exec, s[2:3]
	v_cmp_nlt_f32_e32 vcc, s15, v27
	s_and_saveexec_b64 s[2:3], vcc
	s_cbranch_execnz .LBB0_435

;     __device__ __forceinline__ void operator()(const AccT& acc, const pg8::Unit& u, int wr, int wc, int fr, int fq) const {
;     ...
;                         const int row = row0 + ai * 128 + m * 16;
;                         f32x4 v0 = acc[ai][0][m][0] + b0, v1 = acc[ai][0][m][1] + b1;
; #pragma unroll
;                         for (int e = 0; e < 4; ++e) { v0[e] = v0[e] > 20.f ? v0[e] : log1pf(__expf(v0[e])); v1[e] = v1[e] > 20.f ? v1[e] : log1pf(__expf(v1[e])); }
;                         *(f32x4*)(DTS + (size_t)row * 32 + 8 * fq) = v0; *(f32x4*)(DTS + (size_t)row * 32 + 8 * fq + 4) = v1;
.LBB0_394:
	v_mul_f32_e32 v23, 0x3fb8aa3b, v23
	v_exp_f32_e32 v23, v23
	s_nop 0
	v_add_f32_e32 v30, 1.0, v23
	v_add_f32_e32 v32, -1.0, v30
	v_log_f32_e32 v28, v30
	v_rcp_f32_e32 v32, v32
	v_cmp_neq_f32_e32 vcc, 1.0, v30
	v_mul_f32_e32 v28, 0x3f317218, v28
	v_mul_f32_e32 v32, v23, v32
	v_mul_f32_e32 v28, v28, v32
	v_cndmask_b32_e32 v23, v23, v28, vcc
.LBB0_395:
	s_or_b64 exec, exec, s[2:3]
	v_lshlrev_b64 v[28:29], 7, v[146:147]
	v_lshl_add_u64 v[28:29], v[138:139], 0, v[28:29]
	s_mov_b64 s[2:3], 0x5000
	v_lshl_add_u64 v[30:31], v[28:29], 0, s[2:3]
	v_add_co_u32_e32 v28, vcc, 0x5000, v28
	v_pk_add_f32 v[8:9], v[8:9], v[16:17]
	s_nop 0
	v_addc_co_u32_e32 v29, vcc, 0, v29, vcc
	v_cmp_nlt_f32_e32 vcc, s15, v8
	global_store_dwordx4 v[28:29], v[24:27], off
	global_store_dwordx4 v[30:31], v[20:23], off offset:16
	s_and_saveexec_b64 s[2:3], vcc
	s_cbranch_execz .LBB0_397
	v_mul_f32_e32 v8, 0x3fb8aa3b, v8
	v_exp_f32_e32 v8, v8
	s_nop 0
	v_add_f32_e32 v20, 1.0, v8
	v_add_f32_e32 v22, -1.0, v20
	v_log_f32_e32 v16, v20
	v_rcp_f32_e32 v22, v22
	v_cmp_neq_f32_e32 vcc, 1.0, v20
	v_mul_f32_e32 v16, 0x3f317218, v16
	v_mul_f32_e32 v22, v8, v22
	v_mul_f32_e32 v16, v16, v22
	v_cndmask_b32_e32 v8, v8, v16, vcc
.LBB0_397:
	s_or_b64 exec, exec, s[2:3]
	v_pk_add_f32 v[4:5], v[4:5], v[12:13]
	s_nop 0
	v_cmp_nlt_f32_e32 vcc, s15, v4
	s_and_saveexec_b64 s[2:3], vcc
	s_cbranch_execz .LBB0_399
	v_mul_f32_e32 v4, 0x3fb8aa3b, v4
	v_exp_f32_e32 v4, v4
	s_nop 0
	v_add_f32_e32 v16, 1.0, v4
	v_add_f32_e32 v20, -1.0, v16
	v_log_f32_e32 v12, v16
	v_rcp_f32_e32 v20, v20
	v_cmp_neq_f32_e32 vcc, 1.0, v16
	v_mul_f32_e32 v12, 0x3f317218, v12
	v_mul_f32_e32 v20, v4, v20
	v_mul_f32_e32 v12, v12, v20
	v_cndmask_b32_e32 v4, v4, v12, vcc
.LBB0_399:
	s_or_b64 exec, exec, s[2:3]
	v_pk_add_f32 v[10:11], v[10:11], v[18:19]
	v_cmp_nlt_f32_e32 vcc, s15, v9
	s_and_saveexec_b64 s[2:3], vcc
	s_cbranch_execz .LBB0_401
	v_mul_f32_e32 v9, 0x3fb8aa3b, v9
	v_exp_f32_e32 v9, v9
	s_nop 0
	v_add_f32_e32 v16, 1.0, v9
	v_add_f32_e32 v18, -1.0, v16
	v_log_f32_e32 v12, v16
	v_rcp_f32_e32 v18, v18
	v_cmp_neq_f32_e32 vcc, 1.0, v16
	v_mul_f32_e32 v12, 0x3f317218, v12
	v_mul_f32_e32 v18, v9, v18
	v_mul_f32_e32 v12, v12, v18
	v_cndmask_b32_e32 v9, v9, v12, vcc
.LBB0_401:
	s_or_b64 exec, exec, s[2:3]
	v_pk_add_f32 v[6:7], v[6:7], v[14:15]
	v_cmp_nlt_f32_e32 vcc, s15, v5
	s_and_saveexec_b64 s[2:3], vcc
	s_cbranch_execz .LBB0_436
	v_mul_f32_e32 v5, 0x3fb8aa3b, v5
	v_exp_f32_e32 v5, v5
	s_nop 0
	v_add_f32_e32 v14, 1.0, v5
	v_add_f32_e32 v16, -1.0, v14
	v_log_f32_e32 v12, v14
	v_rcp_f32_e32 v16, v16
	v_cmp_neq_f32_e32 vcc, 1.0, v14
	v_mul_f32_e32 v12, 0x3f317218, v12
	v_mul_f32_e32 v16, v5, v16
	v_mul_f32_e32 v12, v12, v16
	v_cndmask_b32_e32 v5, v5, v12, vcc
	s_or_b64 exec, exec, s[2:3]
	v_cmp_nlt_f32_e32 vcc, s15, v10
	s_and_saveexec_b64 s[2:3], vcc
	s_cbranch_execnz .LBB0_437

;     __device__ __forceinline__ void operator()(const AccT& acc, const pg8::Unit& u, int wr, int wc, int fr, int fq) const {
;     ...
;                         const int row = row0 + ai * 128 + m * 16;
;                         f32x4 v0 = acc[ai][0][m][0] + b0, v1 = acc[ai][0][m][1] + b1;
; #pragma unroll
;                         for (int e = 0; e < 4; ++e) { v0[e] = v0[e] > 20.f ? v0[e] : log1pf(__expf(v0[e])); v1[e] = v1[e] > 20.f ? v1[e] : log1pf(__expf(v1[e])); }
;                         *(f32x4*)(DTS + (size_t)row * 32 + 8 * fq) = v0; *(f32x4*)(DTS + (size_t)row * 32 + 8 * fq + 4) = v1;
.LBB0_404:
	v_mul_f32_e32 v6, 0x3fb8aa3b, v6
	v_exp_f32_e32 v6, v6
	s_nop 0
	v_add_f32_e32 v14, 1.0, v6
	v_add_f32_e32 v16, -1.0, v14
	v_log_f32_e32 v12, v14
	v_rcp_f32_e32 v16, v16
	v_cmp_neq_f32_e32 vcc, 1.0, v14
	v_mul_f32_e32 v12, 0x3f317218, v12
	v_mul_f32_e32 v16, v6, v16
	v_mul_f32_e32 v12, v12, v16
	v_cndmask_b32_e32 v6, v6, v12, vcc
	s_or_b64 exec, exec, s[2:3]
	v_cmp_nlt_f32_e32 vcc, s15, v11
	s_and_saveexec_b64 s[2:3], vcc
	s_cbranch_execnz .LBB0_439

;     __device__ __forceinline__ void operator()(const AccT& acc, const pg8::Unit& u, int wr, int wc, int fr, int fq) const {
;     ...
;                         const int row = row0 + ai * 128 + m * 16;
;                         f32x4 v0 = acc[ai][0][m][0] + b0, v1 = acc[ai][0][m][1] + b1;
; #pragma unroll
;                         for (int e = 0; e < 4; ++e) { v0[e] = v0[e] > 20.f ? v0[e] : log1pf(__expf(v0[e])); v1[e] = v1[e] > 20.f ? v1[e] : log1pf(__expf(v1[e])); }
;                         *(f32x4*)(DTS + (size_t)row * 32 + 8 * fq) = v0; *(f32x4*)(DTS + (size_t)row * 32 + 8 * fq + 4) = v1;
.LBB0_406:
	v_mul_f32_e32 v7, 0x3fb8aa3b, v7
	v_exp_f32_e32 v7, v7
	s_nop 0
	v_add_f32_e32 v14, 1.0, v7
	v_add_f32_e32 v16, -1.0, v14
	v_log_f32_e32 v12, v14
	v_rcp_f32_e32 v16, v16
	v_cmp_neq_f32_e32 vcc, 1.0, v14
	v_mul_f32_e32 v12, 0x3f317218, v12
	v_mul_f32_e32 v16, v7, v16
	v_mul_f32_e32 v12, v12, v16
	v_cndmask_b32_e32 v7, v7, v12, vcc

;     __device__ __forceinline__ void operator()(const AccT& acc, const pg8::Unit& u, int wr, int wc, int fr, int fq) const {
;     ...
;                         const int row = row0 + ai * 128 + m * 16;
;                         f32x4 v0 = acc[ai][0][m][0] + b0, v1 = acc[ai][0][m][1] + b1;
; #pragma unroll
;                         for (int e = 0; e < 4; ++e) { v0[e] = v0[e] > 20.f ? v0[e] : log1pf(__expf(v0[e])); v1[e] = v1[e] > 20.f ? v1[e] : log1pf(__expf(v1[e])); }
;                         *(f32x4*)(DTS + (size_t)row * 32 + 8 * fq) = v0; *(f32x4*)(DTS + (size_t)row * 32 + 8 * fq + 4) = v1;
.LBB0_409:
	v_mul_f32_e32 v74, 0x3fb8aa3b, v74
	v_exp_f32_e32 v74, v74
	s_nop 0
	v_add_f32_e32 v78, 1.0, v74
	v_add_f32_e32 v80, -1.0, v78
	v_log_f32_e32 v76, v78
	v_rcp_f32_e32 v80, v80
	v_cmp_neq_f32_e32 vcc, 1.0, v78
	v_mul_f32_e32 v76, 0x3f317218, v76
	v_mul_f32_e32 v80, v74, v80
	v_mul_f32_e32 v76, v76, v80
	v_cndmask_b32_e32 v74, v74, v76, vcc
	s_or_b64 exec, exec, s[2:3]
	v_cmp_nlt_f32_e32 vcc, s15, v70
	s_and_saveexec_b64 s[2:3], vcc
	s_cbranch_execnz .LBB0_320

;     __device__ __forceinline__ void operator()(const AccT& acc, const pg8::Unit& u, int wr, int wc, int fr, int fq) const {
;     ...
;                         const int row = row0 + ai * 128 + m * 16;
;                         f32x4 v0 = acc[ai][0][m][0] + b0, v1 = acc[ai][0][m][1] + b1;
; #pragma unroll
;                         for (int e = 0; e < 4; ++e) { v0[e] = v0[e] > 20.f ? v0[e] : log1pf(__expf(v0[e])); v1[e] = v1[e] > 20.f ? v1[e] : log1pf(__expf(v1[e])); }
;                         *(f32x4*)(DTS + (size_t)row * 32 + 8 * fq) = v0; *(f32x4*)(DTS + (size_t)row * 32 + 8 * fq + 4) = v1;
.LBB0_411:
	v_mul_f32_e32 v75, 0x3fb8aa3b, v75
	v_exp_f32_e32 v75, v75
	s_nop 0
	v_add_f32_e32 v78, 1.0, v75
	v_add_f32_e32 v80, -1.0, v78
	v_log_f32_e32 v76, v78
	v_rcp_f32_e32 v80, v80
	v_cmp_neq_f32_e32 vcc, 1.0, v78
	v_mul_f32_e32 v76, 0x3f317218, v76
	v_mul_f32_e32 v80, v75, v80
	v_mul_f32_e32 v76, v76, v80
	v_cndmask_b32_e32 v75, v75, v76, vcc
	s_or_b64 exec, exec, s[2:3]
	v_cmp_nlt_f32_e32 vcc, s15, v71
	s_and_saveexec_b64 s[2:3], vcc
	s_cbranch_execnz .LBB0_322
	s_branch .LBB0_323

;     __device__ __forceinline__ void operator()(const AccT& acc, const pg8::Unit& u, int wr, int wc, int fr, int fq) const {
;     ...
;                         const int row = row0 + ai * 128 + m * 16;
;                         f32x4 v0 = acc[ai][0][m][0] + b0, v1 = acc[ai][0][m][1] + b1;
; #pragma unroll
;                         for (int e = 0; e < 4; ++e) { v0[e] = v0[e] > 20.f ? v0[e] : log1pf(__expf(v0[e])); v1[e] = v1[e] > 20.f ? v1[e] : log1pf(__expf(v1[e])); }
;                         *(f32x4*)(DTS + (size_t)row * 32 + 8 * fq) = v0; *(f32x4*)(DTS + (size_t)row * 32 + 8 * fq + 4) = v1;
.LBB0_413:
	v_mul_f32_e32 v66, 0x3fb8aa3b, v66
	v_exp_f32_e32 v66, v66
	s_nop 0
	v_add_f32_e32 v70, 1.0, v66
	v_add_f32_e32 v72, -1.0, v70
	v_log_f32_e32 v68, v70
	v_rcp_f32_e32 v72, v72
	v_cmp_neq_f32_e32 vcc, 1.0, v70
	v_mul_f32_e32 v68, 0x3f317218, v68
	v_mul_f32_e32 v72, v66, v72
	v_mul_f32_e32 v68, v68, v72
	v_cndmask_b32_e32 v66, v66, v68, vcc
	s_or_b64 exec, exec, s[2:3]
	v_cmp_nlt_f32_e32 vcc, s15, v62
	s_and_saveexec_b64 s[2:3], vcc
	s_cbranch_execnz .LBB0_332

;     __device__ __forceinline__ void operator()(const AccT& acc, const pg8::Unit& u, int wr, int wc, int fr, int fq) const {
;     ...
;                         const int row = row0 + ai * 128 + m * 16;
;                         f32x4 v0 = acc[ai][0][m][0] + b0, v1 = acc[ai][0][m][1] + b1;
; #pragma unroll
;                         for (int e = 0; e < 4; ++e) { v0[e] = v0[e] > 20.f ? v0[e] : log1pf(__expf(v0[e])); v1[e] = v1[e] > 20.f ? v1[e] : log1pf(__expf(v1[e])); }
;                         *(f32x4*)(DTS + (size_t)row * 32 + 8 * fq) = v0; *(f32x4*)(DTS + (size_t)row * 32 + 8 * fq + 4) = v1;
.LBB0_415:
	v_mul_f32_e32 v67, 0x3fb8aa3b, v67
	v_exp_f32_e32 v67, v67
	s_nop 0
	v_add_f32_e32 v70, 1.0, v67
	v_add_f32_e32 v72, -1.0, v70
	v_log_f32_e32 v68, v70
	v_rcp_f32_e32 v72, v72
	v_cmp_neq_f32_e32 vcc, 1.0, v70
	v_mul_f32_e32 v68, 0x3f317218, v68
	v_mul_f32_e32 v72, v67, v72
	v_mul_f32_e32 v68, v68, v72
	v_cndmask_b32_e32 v67, v67, v68, vcc
	s_or_b64 exec, exec, s[2:3]
	v_cmp_nlt_f32_e32 vcc, s15, v63
	s_and_saveexec_b64 s[2:3], vcc
	s_cbranch_execnz .LBB0_334
	s_branch .LBB0_335

;     __device__ __forceinline__ void operator()(const AccT& acc, const pg8::Unit& u, int wr, int wc, int fr, int fq) const {
;     ...
;                         const int row = row0 + ai * 128 + m * 16;
;                         f32x4 v0 = acc[ai][0][m][0] + b0, v1 = acc[ai][0][m][1] + b1;
; #pragma unroll
;                         for (int e = 0; e < 4; ++e) { v0[e] = v0[e] > 20.f ? v0[e] : log1pf(__expf(v0[e])); v1[e] = v1[e] > 20.f ? v1[e] : log1pf(__expf(v1[e])); }
;                         *(f32x4*)(DTS + (size_t)row * 32 + 8 * fq) = v0; *(f32x4*)(DTS + (size_t)row * 32 + 8 * fq + 4) = v1;
.LBB0_417:
	v_mul_f32_e32 v58, 0x3fb8aa3b, v58
	v_exp_f32_e32 v58, v58
	s_nop 0
	v_add_f32_e32 v62, 1.0, v58
	v_add_f32_e32 v64, -1.0, v62
	v_log_f32_e32 v60, v62
	v_rcp_f32_e32 v64, v64
	v_cmp_neq_f32_e32 vcc, 1.0, v62
	v_mul_f32_e32 v60, 0x3f317218, v60
	v_mul_f32_e32 v64, v58, v64
	v_mul_f32_e32 v60, v60, v64
	v_cndmask_b32_e32 v58, v58, v60, vcc
	s_or_b64 exec, exec, s[2:3]
	v_cmp_nlt_f32_e32 vcc, s15, v54
	s_and_saveexec_b64 s[2:3], vcc
	s_cbranch_execnz .LBB0_344

;     __device__ __forceinline__ void operator()(const AccT& acc, const pg8::Unit& u, int wr, int wc, int fr, int fq) const {
;     ...
;                         const int row = row0 + ai * 128 + m * 16;
;                         f32x4 v0 = acc[ai][0][m][0] + b0, v1 = acc[ai][0][m][1] + b1;
; #pragma unroll
;                         for (int e = 0; e < 4; ++e) { v0[e] = v0[e] > 20.f ? v0[e] : log1pf(__expf(v0[e])); v1[e] = v1[e] > 20.f ? v1[e] : log1pf(__expf(v1[e])); }
;                         *(f32x4*)(DTS + (size_t)row * 32 + 8 * fq) = v0; *(f32x4*)(DTS + (size_t)row * 32 + 8 * fq + 4) = v1;
.LBB0_419:
	v_mul_f32_e32 v59, 0x3fb8aa3b, v59
	v_exp_f32_e32 v59, v59
	s_nop 0
	v_add_f32_e32 v62, 1.0, v59
	v_add_f32_e32 v64, -1.0, v62
	v_log_f32_e32 v60, v62
	v_rcp_f32_e32 v64, v64
	v_cmp_neq_f32_e32 vcc, 1.0, v62
	v_mul_f32_e32 v60, 0x3f317218, v60
	v_mul_f32_e32 v64, v59, v64
	v_mul_f32_e32 v60, v60, v64
	v_cndmask_b32_e32 v59, v59, v60, vcc
	s_or_b64 exec, exec, s[2:3]
	v_cmp_nlt_f32_e32 vcc, s15, v55
	s_and_saveexec_b64 s[2:3], vcc
	s_cbranch_execnz .LBB0_346
	s_branch .LBB0_347

;     __device__ __forceinline__ void operator()(const AccT& acc, const pg8::Unit& u, int wr, int wc, int fr, int fq) const {
;     ...
;                         const int row = row0 + ai * 128 + m * 16;
;                         f32x4 v0 = acc[ai][0][m][0] + b0, v1 = acc[ai][0][m][1] + b1;
; #pragma unroll
;                         for (int e = 0; e < 4; ++e) { v0[e] = v0[e] > 20.f ? v0[e] : log1pf(__expf(v0[e])); v1[e] = v1[e] > 20.f ? v1[e] : log1pf(__expf(v1[e])); }
;                         *(f32x4*)(DTS + (size_t)row * 32 + 8 * fq) = v0; *(f32x4*)(DTS + (size_t)row * 32 + 8 * fq + 4) = v1;
.LBB0_421:
	v_mul_f32_e32 v50, 0x3fb8aa3b, v50
	v_exp_f32_e32 v50, v50
	s_nop 0
	v_add_f32_e32 v54, 1.0, v50
	v_add_f32_e32 v56, -1.0, v54
	v_log_f32_e32 v52, v54
	v_rcp_f32_e32 v56, v56
	v_cmp_neq_f32_e32 vcc, 1.0, v54
	v_mul_f32_e32 v52, 0x3f317218, v52
	v_mul_f32_e32 v56, v50, v56
	v_mul_f32_e32 v52, v52, v56
	v_cndmask_b32_e32 v50, v50, v52, vcc
	s_or_b64 exec, exec, s[2:3]
	v_cmp_nlt_f32_e32 vcc, s15, v46
	s_and_saveexec_b64 s[2:3], vcc
	s_cbranch_execnz .LBB0_356

;     __device__ __forceinline__ void operator()(const AccT& acc, const pg8::Unit& u, int wr, int wc, int fr, int fq) const {
;     ...
;                         const int row = row0 + ai * 128 + m * 16;
;                         f32x4 v0 = acc[ai][0][m][0] + b0, v1 = acc[ai][0][m][1] + b1;
; #pragma unroll
;                         for (int e = 0; e < 4; ++e) { v0[e] = v0[e] > 20.f ? v0[e] : log1pf(__expf(v0[e])); v1[e] = v1[e] > 20.f ? v1[e] : log1pf(__expf(v1[e])); }
;                         *(f32x4*)(DTS + (size_t)row * 32 + 8 * fq) = v0; *(f32x4*)(DTS + (size_t)row * 32 + 8 * fq + 4) = v1;
.LBB0_423:
	v_mul_f32_e32 v51, 0x3fb8aa3b, v51
	v_exp_f32_e32 v51, v51
	s_nop 0
	v_add_f32_e32 v54, 1.0, v51
	v_add_f32_e32 v56, -1.0, v54
	v_log_f32_e32 v52, v54
	v_rcp_f32_e32 v56, v56
	v_cmp_neq_f32_e32 vcc, 1.0, v54
	v_mul_f32_e32 v52, 0x3f317218, v52
	v_mul_f32_e32 v56, v51, v56
	v_mul_f32_e32 v52, v52, v56
	v_cndmask_b32_e32 v51, v51, v52, vcc
	s_or_b64 exec, exec, s[2:3]
	v_cmp_nlt_f32_e32 vcc, s15, v47
	s_and_saveexec_b64 s[2:3], vcc
	s_cbranch_execnz .LBB0_358
	s_branch .LBB0_359

;     __device__ __forceinline__ void operator()(const AccT& acc, const pg8::Unit& u, int wr, int wc, int fr, int fq) const {
;     ...
;                         const int row = row0 + ai * 128 + m * 16;
;                         f32x4 v0 = acc[ai][0][m][0] + b0, v1 = acc[ai][0][m][1] + b1;
; #pragma unroll
;                         for (int e = 0; e < 4; ++e) { v0[e] = v0[e] > 20.f ? v0[e] : log1pf(__expf(v0[e])); v1[e] = v1[e] > 20.f ? v1[e] : log1pf(__expf(v1[e])); }
;                         *(f32x4*)(DTS + (size_t)row * 32 + 8 * fq) = v0; *(f32x4*)(DTS + (size_t)row * 32 + 8 * fq + 4) = v1;
.LBB0_425:
	v_mul_f32_e32 v42, 0x3fb8aa3b, v42
	v_exp_f32_e32 v42, v42
	s_nop 0
	v_add_f32_e32 v46, 1.0, v42
	v_add_f32_e32 v48, -1.0, v46
	v_log_f32_e32 v44, v46
	v_rcp_f32_e32 v48, v48
	v_cmp_neq_f32_e32 vcc, 1.0, v46
	v_mul_f32_e32 v44, 0x3f317218, v44
	v_mul_f32_e32 v48, v42, v48
	v_mul_f32_e32 v44, v44, v48
	v_cndmask_b32_e32 v42, v42, v44, vcc
	s_or_b64 exec, exec, s[2:3]
	v_cmp_nlt_f32_e32 vcc, s15, v38
	s_and_saveexec_b64 s[2:3], vcc
	s_cbranch_execnz .LBB0_368

;     __device__ __forceinline__ void operator()(const AccT& acc, const pg8::Unit& u, int wr, int wc, int fr, int fq) const {
;     ...
;                         const int row = row0 + ai * 128 + m * 16;
;                         f32x4 v0 = acc[ai][0][m][0] + b0, v1 = acc[ai][0][m][1] + b1;
; #pragma unroll
;                         for (int e = 0; e < 4; ++e) { v0[e] = v0[e] > 20.f ? v0[e] : log1pf(__expf(v0[e])); v1[e] = v1[e] > 20.f ? v1[e] : log1pf(__expf(v1[e])); }
;                         *(f32x4*)(DTS + (size_t)row * 32 + 8 * fq) = v0; *(f32x4*)(DTS + (size_t)row * 32 + 8 * fq + 4) = v1;
.LBB0_427:
	v_mul_f32_e32 v43, 0x3fb8aa3b, v43
	v_exp_f32_e32 v43, v43
	s_nop 0
	v_add_f32_e32 v46, 1.0, v43
	v_add_f32_e32 v48, -1.0, v46
	v_log_f32_e32 v44, v46
	v_rcp_f32_e32 v48, v48
	v_cmp_neq_f32_e32 vcc, 1.0, v46
	v_mul_f32_e32 v44, 0x3f317218, v44
	v_mul_f32_e32 v48, v43, v48
	v_mul_f32_e32 v44, v44, v48
	v_cndmask_b32_e32 v43, v43, v44, vcc
	s_or_b64 exec, exec, s[2:3]
	v_cmp_nlt_f32_e32 vcc, s15, v39
	s_and_saveexec_b64 s[2:3], vcc
	s_cbranch_execnz .LBB0_370
	s_branch .LBB0_371

;     __device__ __forceinline__ void operator()(const AccT& acc, const pg8::Unit& u, int wr, int wc, int fr, int fq) const {
;     ...
;                         const int row = row0 + ai * 128 + m * 16;
;                         f32x4 v0 = acc[ai][0][m][0] + b0, v1 = acc[ai][0][m][1] + b1;
; #pragma unroll
;                         for (int e = 0; e < 4; ++e) { v0[e] = v0[e] > 20.f ? v0[e] : log1pf(__expf(v0[e])); v1[e] = v1[e] > 20.f ? v1[e] : log1pf(__expf(v1[e])); }
;                         *(f32x4*)(DTS + (size_t)row * 32 + 8 * fq) = v0; *(f32x4*)(DTS + (size_t)row * 32 + 8 * fq + 4) = v1;
.LBB0_429:
	v_mul_f32_e32 v34, 0x3fb8aa3b, v34
	v_exp_f32_e32 v34, v34
	s_nop 0
	v_add_f32_e32 v38, 1.0, v34
	v_add_f32_e32 v40, -1.0, v38
	v_log_f32_e32 v36, v38
	v_rcp_f32_e32 v40, v40
	v_cmp_neq_f32_e32 vcc, 1.0, v38
	v_mul_f32_e32 v36, 0x3f317218, v36
	v_mul_f32_e32 v40, v34, v40
	v_mul_f32_e32 v36, v36, v40
	v_cndmask_b32_e32 v34, v34, v36, vcc
	s_or_b64 exec, exec, s[2:3]
	v_cmp_nlt_f32_e32 vcc, s15, v30
	s_and_saveexec_b64 s[2:3], vcc
	s_cbranch_execnz .LBB0_380

;     __device__ __forceinline__ void operator()(const AccT& acc, const pg8::Unit& u, int wr, int wc, int fr, int fq) const {
;     ...
;                         const int row = row0 + ai * 128 + m * 16;
;                         f32x4 v0 = acc[ai][0][m][0] + b0, v1 = acc[ai][0][m][1] + b1;
; #pragma unroll
;                         for (int e = 0; e < 4; ++e) { v0[e] = v0[e] > 20.f ? v0[e] : log1pf(__expf(v0[e])); v1[e] = v1[e] > 20.f ? v1[e] : log1pf(__expf(v1[e])); }
;                         *(f32x4*)(DTS + (size_t)row * 32 + 8 * fq) = v0; *(f32x4*)(DTS + (size_t)row * 32 + 8 * fq + 4) = v1;
.LBB0_431:
	v_mul_f32_e32 v35, 0x3fb8aa3b, v35
	v_exp_f32_e32 v35, v35
	s_nop 0
	v_add_f32_e32 v38, 1.0, v35
	v_add_f32_e32 v40, -1.0, v38
	v_log_f32_e32 v36, v38
	v_rcp_f32_e32 v40, v40
	v_cmp_neq_f32_e32 vcc, 1.0, v38
	v_mul_f32_e32 v36, 0x3f317218, v36
	v_mul_f32_e32 v40, v35, v40
	v_mul_f32_e32 v36, v36, v40
	v_cndmask_b32_e32 v35, v35, v36, vcc
	s_or_b64 exec, exec, s[2:3]
	v_cmp_nlt_f32_e32 vcc, s15, v31
	s_and_saveexec_b64 s[2:3], vcc
	s_cbranch_execnz .LBB0_382
	s_branch .LBB0_383

;     __device__ __forceinline__ void operator()(const AccT& acc, const pg8::Unit& u, int wr, int wc, int fr, int fq) const {
;     ...
;                         const int row = row0 + ai * 128 + m * 16;
;                         f32x4 v0 = acc[ai][0][m][0] + b0, v1 = acc[ai][0][m][1] + b1;
; #pragma unroll
;                         for (int e = 0; e < 4; ++e) { v0[e] = v0[e] > 20.f ? v0[e] : log1pf(__expf(v0[e])); v1[e] = v1[e] > 20.f ? v1[e] : log1pf(__expf(v1[e])); }
;                         *(f32x4*)(DTS + (size_t)row * 32 + 8 * fq) = v0; *(f32x4*)(DTS + (size_t)row * 32 + 8 * fq + 4) = v1;
.LBB0_433:
	v_mul_f32_e32 v26, 0x3fb8aa3b, v26
	v_exp_f32_e32 v26, v26
	s_nop 0
	v_add_f32_e32 v30, 1.0, v26
	v_add_f32_e32 v32, -1.0, v30
	v_log_f32_e32 v28, v30
	v_rcp_f32_e32 v32, v32
	v_cmp_neq_f32_e32 vcc, 1.0, v30
	v_mul_f32_e32 v28, 0x3f317218, v28
	v_mul_f32_e32 v32, v26, v32
	v_mul_f32_e32 v28, v28, v32
	v_cndmask_b32_e32 v26, v26, v28, vcc
	s_or_b64 exec, exec, s[2:3]
	v_cmp_nlt_f32_e32 vcc, s15, v22
	s_and_saveexec_b64 s[2:3], vcc
	s_cbranch_execnz .LBB0_392

;     __device__ __forceinline__ void operator()(const AccT& acc, const pg8::Unit& u, int wr, int wc, int fr, int fq) const {
;     ...
;                         const int row = row0 + ai * 128 + m * 16;
;                         f32x4 v0 = acc[ai][0][m][0] + b0, v1 = acc[ai][0][m][1] + b1;
; #pragma unroll
;                         for (int e = 0; e < 4; ++e) { v0[e] = v0[e] > 20.f ? v0[e] : log1pf(__expf(v0[e])); v1[e] = v1[e] > 20.f ? v1[e] : log1pf(__expf(v1[e])); }
;                         *(f32x4*)(DTS + (size_t)row * 32 + 8 * fq) = v0; *(f32x4*)(DTS + (size_t)row * 32 + 8 * fq + 4) = v1;
.LBB0_435:
	v_mul_f32_e32 v27, 0x3fb8aa3b, v27
	v_exp_f32_e32 v27, v27
	s_nop 0
	v_add_f32_e32 v30, 1.0, v27
	v_add_f32_e32 v32, -1.0, v30
	v_log_f32_e32 v28, v30
	v_rcp_f32_e32 v32, v32
	v_cmp_neq_f32_e32 vcc, 1.0, v30
	v_mul_f32_e32 v28, 0x3f317218, v28
	v_mul_f32_e32 v32, v27, v32
	v_mul_f32_e32 v28, v28, v32
	v_cndmask_b32_e32 v27, v27, v28, vcc
	s_or_b64 exec, exec, s[2:3]
	v_cmp_nlt_f32_e32 vcc, s15, v23
	s_and_saveexec_b64 s[2:3], vcc
	s_cbranch_execnz .LBB0_394
	s_branch .LBB0_395

;     __device__ __forceinline__ void operator()(const AccT& acc, const pg8::Unit& u, int wr, int wc, int fr, int fq) const {
;     ...
;                         const int row = row0 + ai * 128 + m * 16;
;                         f32x4 v0 = acc[ai][0][m][0] + b0, v1 = acc[ai][0][m][1] + b1;
; #pragma unroll
;                         for (int e = 0; e < 4; ++e) { v0[e] = v0[e] > 20.f ? v0[e] : log1pf(__expf(v0[e])); v1[e] = v1[e] > 20.f ? v1[e] : log1pf(__expf(v1[e])); }
;                         *(f32x4*)(DTS + (size_t)row * 32 + 8 * fq) = v0; *(f32x4*)(DTS + (size_t)row * 32 + 8 * fq + 4) = v1;
.LBB0_437:
	v_mul_f32_e32 v10, 0x3fb8aa3b, v10
	v_exp_f32_e32 v10, v10
	s_nop 0
	v_add_f32_e32 v14, 1.0, v10
	v_add_f32_e32 v16, -1.0, v14
	v_log_f32_e32 v12, v14
	v_rcp_f32_e32 v16, v16
	v_cmp_neq_f32_e32 vcc, 1.0, v14
	v_mul_f32_e32 v12, 0x3f317218, v12
	v_mul_f32_e32 v16, v10, v16
	v_mul_f32_e32 v12, v12, v16
	v_cndmask_b32_e32 v10, v10, v12, vcc
	s_or_b64 exec, exec, s[2:3]
	v_cmp_nlt_f32_e32 vcc, s15, v6
	s_and_saveexec_b64 s[2:3], vcc
	s_cbranch_execnz .LBB0_404

;     __device__ __forceinline__ void operator()(const AccT& acc, const pg8::Unit& u, int wr, int wc, int fr, int fq) const {
;     ...
;                         const int row = row0 + ai * 128 + m * 16;
;                         f32x4 v0 = acc[ai][0][m][0] + b0, v1 = acc[ai][0][m][1] + b1;
; #pragma unroll
;                         for (int e = 0; e < 4; ++e) { v0[e] = v0[e] > 20.f ? v0[e] : log1pf(__expf(v0[e])); v1[e] = v1[e] > 20.f ? v1[e] : log1pf(__expf(v1[e])); }
;                         *(f32x4*)(DTS + (size_t)row * 32 + 8 * fq) = v0; *(f32x4*)(DTS + (size_t)row * 32 + 8 * fq + 4) = v1;
.LBB0_439:
	v_mul_f32_e32 v11, 0x3fb8aa3b, v11
	v_exp_f32_e32 v11, v11
	s_nop 0
	v_add_f32_e32 v14, 1.0, v11
	v_add_f32_e32 v16, -1.0, v14
	v_log_f32_e32 v12, v14
	v_rcp_f32_e32 v16, v16
	v_cmp_neq_f32_e32 vcc, 1.0, v14
	v_mul_f32_e32 v12, 0x3f317218, v12
	v_mul_f32_e32 v16, v11, v16
	v_mul_f32_e32 v12, v12, v16
	v_cndmask_b32_e32 v11, v11, v12, vcc
	s_or_b64 exec, exec, s[2:3]
	v_cmp_nlt_f32_e32 vcc, s15, v7
	s_and_saveexec_b64 s[2:3], vcc
	s_cbranch_execnz .LBB0_406
	s_branch .LBB0_407
